# leader is the 65th arriving wave of its XCD instead of the first
# baseline (speedup 1.0000x reference)
.LBB0_598:
	s_barrier
	v_and_b32_e32 v249, 2, v60
	v_cmp_eq_u32_e64 s[6:7], 0, v249
	v_and_b32_e32 v249, 1, v60
	v_cmp_eq_u32_e64 s[0:1], 0, v249
	v_mov_b32_e32 v253, 0
	v_mov_b32_e32 v147, 0
	v_mov_b32_e32 v148, 0
	v_mov_b32_e32 v244, 0
	v_lshlrev_b32_e32 v248, 10, v58
	v_lshl_add_u32 v248, v60, 4, v248
	s_getreg_b32 s2, hwreg(HW_REG_XCC_ID)
	s_and_b32 s2, s2, 7
	s_lshl_b32 s2, s2, 7
	s_add_u32 s2, s2, s44
	s_addc_u32 s3, s45, 0
	s_add_u32 s2, s2, 0xffff8100
	s_addc_u32 s3, s3, -1
	v_mov_b32_e32 v246, s2
	v_mov_b32_e32 v247, s3
	v_mov_b32_e32 v250, 1
	s_mov_b64 exec, 1
	global_atomic_add v251, v[246:247], v250, off offset:1792 sc0
	s_mov_b64 exec, -1
	s_waitcnt vmcnt(0)
	v_readfirstlane_b32 s2, v251
	s_cmp_eq_u32 s2, 64
	s_cselect_b32 s82, 1, 0
	s_and_b32 s79, s2, 1
	s_lshl_b32 s79, s79, 10
	s_lshr_b32 s78, s2, 1
	s_and_b32 s78, s78, 0x7f
	s_add_i32 s78, s78, 768
	s_mov_b32 s23, 0
